# delta-rule solve: wait gaps between dependent f32 MFMA groups shortened from 24 to 16 states (10 required); rest as the previous version
# speedup vs baseline: 1.0040x; 1.0002x over previous
.Ldm_not:
	s_waitcnt lgkmcnt(0)
	s_barrier
	v_lshlrev_b32_e32 v211, 8, v201
	v_lshl_add_u32 v211, v210, 4, v211
	v_add_u32_e32 v211, 0x17c00, v211
	v_lshlrev_b32_e32 v212, 6, v201
	v_lshl_add_u32 v212, v210, 4, v212
	v_add_u32_e32 v212, 0x24800, v212
	ds_read_b128 v[36:39], v212
	ds_read_b128 v[40:43], v212 offset:1024
	ds_read_b128 v[44:47], v212 offset:2048
	ds_read_b128 v[86:89], v212 offset:3072
	ds_read_b128 v[168:171], v211 offset:4096
	ds_read_b128 v[172:175], v211 offset:8192
	ds_read_b128 v[176:179], v211 offset:8256
	ds_read_b128 v[180:183], v211 offset:12288
	ds_read_b128 v[184:187], v211 offset:12352
	ds_read_b128 v[32:35], v211 offset:12416
	v_mov_b32_e32 v136, 0
	v_mov_b32_e32 v137, 0
	v_mov_b32_e32 v138, 0
	v_mov_b32_e32 v139, 0
	v_mov_b32_e32 v140, 0
	v_mov_b32_e32 v141, 0
	v_mov_b32_e32 v142, 0
	v_mov_b32_e32 v143, 0
	v_mov_b32_e32 v144, 0
	v_mov_b32_e32 v145, 0
	v_mov_b32_e32 v146, 0
	v_mov_b32_e32 v147, 0
	v_mov_b32_e32 v148, 0
	v_mov_b32_e32 v149, 0
	v_mov_b32_e32 v150, 0
	v_mov_b32_e32 v151, 0
	v_mov_b32_e32 v152, 0
	v_mov_b32_e32 v153, 0
	v_mov_b32_e32 v154, 0
	v_mov_b32_e32 v155, 0
	v_mov_b32_e32 v156, 0
	v_mov_b32_e32 v157, 0
	v_mov_b32_e32 v158, 0
	v_mov_b32_e32 v159, 0
	v_mov_b32_e32 v160, 0
	v_mov_b32_e32 v161, 0
	v_mov_b32_e32 v162, 0
	v_mov_b32_e32 v163, 0
	v_mov_b32_e32 v164, 0
	v_mov_b32_e32 v165, 0
	v_mov_b32_e32 v166, 0
	v_mov_b32_e32 v167, 0
	s_waitcnt lgkmcnt(0)
	v_mfma_f32_16x16x4_f32 v[136:139], v36, v104, v[136:139]
	v_mfma_f32_16x16x4_f32 v[140:143], v36, v108, v[140:143]
	v_mfma_f32_16x16x4_f32 v[136:139], v37, v105, v[136:139]
	v_mfma_f32_16x16x4_f32 v[140:143], v37, v109, v[140:143]
	v_mfma_f32_16x16x4_f32 v[136:139], v38, v106, v[136:139]
	v_mfma_f32_16x16x4_f32 v[140:143], v38, v110, v[140:143]
	v_mfma_f32_16x16x4_f32 v[136:139], v39, v107, v[136:139]
	v_mfma_f32_16x16x4_f32 v[140:143], v39, v111, v[140:143]
	s_nop 7
	s_nop 7
	v_mfma_f32_16x16x4_f32 v[112:115], v168, v136, v[112:115]
	v_mfma_f32_16x16x4_f32 v[116:119], v168, v140, v[116:119]
	v_mfma_f32_16x16x4_f32 v[112:115], v169, v137, v[112:115]
	v_mfma_f32_16x16x4_f32 v[116:119], v169, v141, v[116:119]
	v_mfma_f32_16x16x4_f32 v[112:115], v170, v138, v[112:115]
	v_mfma_f32_16x16x4_f32 v[116:119], v170, v142, v[116:119]
	v_mfma_f32_16x16x4_f32 v[112:115], v171, v139, v[112:115]
	v_mfma_f32_16x16x4_f32 v[116:119], v171, v143, v[116:119]
	s_nop 7
	s_nop 7
	v_mfma_f32_16x16x4_f32 v[144:147], v40, v112, v[144:147]
	v_mfma_f32_16x16x4_f32 v[148:151], v40, v116, v[148:151]
	v_mfma_f32_16x16x4_f32 v[144:147], v41, v113, v[144:147]
	v_mfma_f32_16x16x4_f32 v[148:151], v41, v117, v[148:151]
	v_mfma_f32_16x16x4_f32 v[144:147], v42, v114, v[144:147]
	v_mfma_f32_16x16x4_f32 v[148:151], v42, v118, v[148:151]
	v_mfma_f32_16x16x4_f32 v[144:147], v43, v115, v[144:147]
	v_mfma_f32_16x16x4_f32 v[148:151], v43, v119, v[148:151]
	s_nop 7
	s_nop 7
	v_mfma_f32_16x16x4_f32 v[120:123], v172, v136, v[120:123]
	v_mfma_f32_16x16x4_f32 v[124:127], v172, v140, v[124:127]
	v_mfma_f32_16x16x4_f32 v[120:123], v173, v137, v[120:123]
	v_mfma_f32_16x16x4_f32 v[124:127], v173, v141, v[124:127]
	v_mfma_f32_16x16x4_f32 v[120:123], v174, v138, v[120:123]
	v_mfma_f32_16x16x4_f32 v[124:127], v174, v142, v[124:127]
	v_mfma_f32_16x16x4_f32 v[120:123], v175, v139, v[120:123]
	v_mfma_f32_16x16x4_f32 v[124:127], v175, v143, v[124:127]
	v_mfma_f32_16x16x4_f32 v[120:123], v176, v144, v[120:123]
	v_mfma_f32_16x16x4_f32 v[124:127], v176, v148, v[124:127]
	v_mfma_f32_16x16x4_f32 v[120:123], v177, v145, v[120:123]
	v_mfma_f32_16x16x4_f32 v[124:127], v177, v149, v[124:127]
	v_mfma_f32_16x16x4_f32 v[120:123], v178, v146, v[120:123]
	v_mfma_f32_16x16x4_f32 v[124:127], v178, v150, v[124:127]
	v_mfma_f32_16x16x4_f32 v[120:123], v179, v147, v[120:123]
	v_mfma_f32_16x16x4_f32 v[124:127], v179, v151, v[124:127]
	s_nop 7
	s_nop 7
	v_mfma_f32_16x16x4_f32 v[152:155], v44, v120, v[152:155]
	v_mfma_f32_16x16x4_f32 v[156:159], v44, v124, v[156:159]
	v_mfma_f32_16x16x4_f32 v[152:155], v45, v121, v[152:155]
	v_mfma_f32_16x16x4_f32 v[156:159], v45, v125, v[156:159]
	v_mfma_f32_16x16x4_f32 v[152:155], v46, v122, v[152:155]
	v_mfma_f32_16x16x4_f32 v[156:159], v46, v126, v[156:159]
	v_mfma_f32_16x16x4_f32 v[152:155], v47, v123, v[152:155]
	v_mfma_f32_16x16x4_f32 v[156:159], v47, v127, v[156:159]
	s_nop 7
	s_nop 7
	v_mfma_f32_16x16x4_f32 v[128:131], v180, v136, v[128:131]
	v_mfma_f32_16x16x4_f32 v[132:135], v180, v140, v[132:135]
	v_mfma_f32_16x16x4_f32 v[128:131], v181, v137, v[128:131]
	v_mfma_f32_16x16x4_f32 v[132:135], v181, v141, v[132:135]
	v_mfma_f32_16x16x4_f32 v[128:131], v182, v138, v[128:131]
	v_mfma_f32_16x16x4_f32 v[132:135], v182, v142, v[132:135]
	v_mfma_f32_16x16x4_f32 v[128:131], v183, v139, v[128:131]
	v_mfma_f32_16x16x4_f32 v[132:135], v183, v143, v[132:135]
	v_mfma_f32_16x16x4_f32 v[128:131], v184, v144, v[128:131]
	v_mfma_f32_16x16x4_f32 v[132:135], v184, v148, v[132:135]
	v_mfma_f32_16x16x4_f32 v[128:131], v185, v145, v[128:131]
	v_mfma_f32_16x16x4_f32 v[132:135], v185, v149, v[132:135]
	v_mfma_f32_16x16x4_f32 v[128:131], v186, v146, v[128:131]
	v_mfma_f32_16x16x4_f32 v[132:135], v186, v150, v[132:135]
	v_mfma_f32_16x16x4_f32 v[128:131], v187, v147, v[128:131]
	v_mfma_f32_16x16x4_f32 v[132:135], v187, v151, v[132:135]
	v_mfma_f32_16x16x4_f32 v[128:131], v32, v152, v[128:131]
	v_mfma_f32_16x16x4_f32 v[132:135], v32, v156, v[132:135]
	v_mfma_f32_16x16x4_f32 v[128:131], v33, v153, v[128:131]
	v_mfma_f32_16x16x4_f32 v[132:135], v33, v157, v[132:135]
	v_mfma_f32_16x16x4_f32 v[128:131], v34, v154, v[128:131]
	v_mfma_f32_16x16x4_f32 v[132:135], v34, v158, v[132:135]
	v_mfma_f32_16x16x4_f32 v[128:131], v35, v155, v[128:131]
	v_mfma_f32_16x16x4_f32 v[132:135], v35, v159, v[132:135]
	s_nop 7
	s_nop 7
	v_mfma_f32_16x16x4_f32 v[160:163], v86, v128, v[160:163]
	v_mfma_f32_16x16x4_f32 v[164:167], v86, v132, v[164:167]
	v_mfma_f32_16x16x4_f32 v[160:163], v87, v129, v[160:163]
	v_mfma_f32_16x16x4_f32 v[164:167], v87, v133, v[164:167]
	v_mfma_f32_16x16x4_f32 v[160:163], v88, v130, v[160:163]
	v_mfma_f32_16x16x4_f32 v[164:167], v88, v134, v[164:167]
	v_mfma_f32_16x16x4_f32 v[160:163], v89, v131, v[160:163]
	v_mfma_f32_16x16x4_f32 v[164:167], v89, v135, v[164:167]
	s_nop 7
	s_nop 7
	s_cmp_ge_u32 s91, 4
	v_cvt_pk_bf16_f32 v213, v136, 0
	v_cvt_pk_bf16_f32 v214, v137, 0
	v_cvt_pk_bf16_f32 v215, v138, 0
	v_cvt_pk_bf16_f32 v216, v139, 0
	v_cvt_pk_bf16_f32 v217, v140, 0
	v_cvt_pk_bf16_f32 v218, v141, 0
	v_cvt_pk_bf16_f32 v219, v142, 0
	v_cvt_pk_bf16_f32 v220, v143, 0
	v_cvt_pk_bf16_f32 v221, v144, 0
	v_cvt_pk_bf16_f32 v222, v145, 0
	v_cvt_pk_bf16_f32 v223, v146, 0
	v_cvt_pk_bf16_f32 v224, v147, 0
	v_cvt_pk_bf16_f32 v225, v148, 0
	v_cvt_pk_bf16_f32 v226, v149, 0
	v_cvt_pk_bf16_f32 v227, v150, 0
	v_cvt_pk_bf16_f32 v228, v151, 0
	v_cvt_pk_bf16_f32 v229, v152, 0
	v_cvt_pk_bf16_f32 v230, v153, 0
	v_cvt_pk_bf16_f32 v231, v154, 0
	v_cvt_pk_bf16_f32 v232, v155, 0
	v_cvt_pk_bf16_f32 v233, v156, 0
	v_cvt_pk_bf16_f32 v234, v157, 0
	v_cvt_pk_bf16_f32 v235, v158, 0
	v_cvt_pk_bf16_f32 v236, v159, 0
	v_cvt_pk_bf16_f32 v237, v160, 0
	v_cvt_pk_bf16_f32 v238, v161, 0
	v_cvt_pk_bf16_f32 v239, v162, 0
	v_cvt_pk_bf16_f32 v240, v163, 0
	v_cvt_pk_bf16_f32 v241, v164, 0
	v_cvt_pk_bf16_f32 v242, v165, 0
	v_cvt_pk_bf16_f32 v243, v166, 0
	v_cvt_pk_bf16_f32 v244, v167, 0
	s_cbranch_scc1 .Ldm_kout
	ds_write_b16 v245, v213
	ds_write_b16 v245, v214 offset:256
	ds_write_b16 v245, v215 offset:512
	ds_write_b16 v245, v216 offset:768
	ds_write_b16 v245, v217 offset:32
	ds_write_b16 v245, v218 offset:288
	ds_write_b16 v245, v219 offset:544
	ds_write_b16 v245, v220 offset:800
	s_waitcnt lgkmcnt(7)
	ds_write_b16 v245, v221 offset:4096
	ds_write_b16 v245, v222 offset:4352
	ds_write_b16 v245, v223 offset:4608
	ds_write_b16 v245, v224 offset:4864
	ds_write_b16 v245, v225 offset:4128
	ds_write_b16 v245, v226 offset:4384
	ds_write_b16 v245, v227 offset:4640
	ds_write_b16 v245, v228 offset:4896
	s_waitcnt lgkmcnt(7)
	ds_write_b16 v245, v229 offset:8192
	ds_write_b16 v245, v230 offset:8448
	ds_write_b16 v245, v231 offset:8704
	ds_write_b16 v245, v232 offset:8960
	ds_write_b16 v245, v233 offset:8224
	ds_write_b16 v245, v234 offset:8480
	ds_write_b16 v245, v235 offset:8736
	ds_write_b16 v245, v236 offset:8992
	s_waitcnt lgkmcnt(7)
	ds_write_b16 v245, v237 offset:12288
	ds_write_b16 v245, v238 offset:12544
	ds_write_b16 v245, v239 offset:12800
	ds_write_b16 v245, v240 offset:13056
	ds_write_b16 v245, v241 offset:12320
	ds_write_b16 v245, v242 offset:12576
	ds_write_b16 v245, v243 offset:12832
	ds_write_b16 v245, v244 offset:13088
	s_waitcnt lgkmcnt(7)
	s_branch .Ldm_done
